# DA loop: bias class from two per-unit thresholds and a single tile counter (5 fewer scalar ops per tile in the PV gaps)
# speedup vs baseline: 1.0006x; 1.0006x over previous
; __device__ __forceinline__ void da_phase(LAS unsigned char* lds, const bf16* Q, const bf16* Kb, const bf16* Vb, bf16* O, const float* lq1, const float* lk1, const float* lq2, const float* lk2,
;                                          const float* t5, int G, int wave, int lane, int tid) {
;     ...
;         const int qrow0 = qb * 128 + 32 * w4;
;         H8 qf[4];
; #pragma unroll
;         for (int d0 = 0; d0 < 4; ++d0) qf[d0] = *(const GASP H8*)(Q + ((size_t)h * T + tok0 + qrow0 + r32) * 128 + comp * 64 + 16 * d0 + 8 * hi);
;         float m = 0.f, l = 0.f; F16 o[4];
; #pragma unroll
;         for (int db = 0; db < 4; ++db) o[db] = F16{};
;         int cur_cls = -1; float cb = 0.f, cbm = 0.f;
;         U4 pw[4] = {};
;         const int NT = S / 64;
;         const char* kub = (const char*)Kb + (((size_t)h * T + tok0 + 32 * (wave & 1)) * 128 + (wave >> 2) * 64 + ((wave >> 1) & 1) * 32) * 2;
;         const char* vub = (const char*)Vb + (((size_t)h * T + tok0 + 16 * ((2 * wave) & 3)) * 128 + ((2 * wave) >> 2) * 32) * 2;
;         const unsigned kofs = (unsigned)(((lane >> 2) * 128 + ((lane & 3) ^ ((lane >> 4) & 3)) * 8) * 2);
;         const unsigned vofs = (unsigned)(((lane >> 2) * 128 + (lane & 3) * 8) * 2);
;     ...
;         DA_DMA(0, 0, 0); DA_DMA(1, 1, 1);
;         int ks_cur = 0, ks_n2 = 2;
;         const unsigned kswz = (unsigned)((hi ^ ((r32 >> 2) & 3)) * 16);
;         const unsigned ka_base = ldsb + KS + comp * 8192 + r32 * 64;
;         S4 va[8], vb[8];
; #pragma unroll 1
;         for (int t = 0; t < NT; ++t) {
;             if (t + 1 < NT) asm volatile("s_waitcnt vmcnt(4)" ::: "memory"); else asm volatile("s_waitcnt vmcnt(0)" ::: "memory");
;             __builtin_amdgcn_s_barrier();
;             asm volatile("" ::: "memory");
;             const unsigned vaddr_p = ldsb + VS + ((t == 0 ? 0 : t + 3) & 3) * 16384 + vlane;
;             U4 kf[4];
;             const unsigned ka0 = ka_base + ks_cur * 16384 + kswz, ka1 = ka_base + ks_cur * 16384 + (kswz ^ 32u);
;             DS_RD128(kf[0], ka0, 0); DS_RD128(kf[1], ka1, 0); DS_RD128(kf[2], ka0, 4096); DS_RD128(kf[3], ka1, 4096);
;             DA_VREADS(va, vaddr_p, 0); DA_VREADS(vb, vaddr_p, 1);
;             const int kv0 = 64 * t; const int relmin = kv0 - (qrow0 + 31), relmax = kv0 + 63 - qrow0;
;             const int cls = 1 + (relmin >= 128 ? 1 : 0) - (relmax <= -128 ? 1 : 0);
.LBB0_201:
	s_lshl_b32 s18, s38, 7
	v_readlane_b32 s0, v254, 47
	s_or_b32 s38, s18, s0
	s_mul_i32 s10, s36, 0x18000
	s_add_u32 s0, s10, s38
	s_addc_u32 s1, 0, 0
	s_add_u32 s0, s0, s14
	s_addc_u32 s1, s1, s15
	v_lshl_add_u64 v[2:3], s[0:1], 0, v[188:189]
	v_readlane_b32 s0, v254, 20
	s_add_u32 s0, s14, s0
	s_addc_u32 s1, s15, 0
	s_add_u32 s0, s0, s10
	s_addc_u32 s1, s1, 0
	s_lshl_b64 s[0:1], s[0:1], 8
	v_lshlrev_b64 v[2:3], 8, v[2:3]
	s_add_u32 s10, s34, s0
	v_lshl_add_u64 v[2:3], v[192:193], 0, v[2:3]
	s_addc_u32 s11, s35, s1
	s_mov_b32 m0, s3
	global_load_dwordx4 v[120:123], v[2:3], off
	global_load_dwordx4 v[124:127], v[2:3], off offset:32
	global_load_dwordx4 v[128:131], v[2:3], off offset:64
	global_load_dwordx4 v[132:135], v[2:3], off offset:96
	s_add_u32 s16, s30, s0
	v_lshl_add_u64 v[2:3], s[10:11], 0, v[194:195]
	s_addc_u32 s17, s31, s1
	global_load_lds_dwordx4 v[2:3], off
	v_lshl_add_u64 v[4:5], v[2:3], 0, s[62:63]
	s_add_i32 m0, s3, 0x400
	s_mov_b64 s[10:11], 0x4000
	global_load_lds_dwordx4 v[4:5], off
	v_lshl_add_u64 v[4:5], s[16:17], 0, v[196:197]
	s_add_i32 m0, s3, 0xc000
	v_lshl_add_u64 v[6:7], v[4:5], 0, s[62:63]
	global_load_lds_dwordx4 v[4:5], off
	s_add_i32 m0, s3, 0xc400
	s_mov_b64 s[16:17], 0x5000
	global_load_lds_dwordx4 v[6:7], off
	v_lshl_add_u64 v[6:7], v[2:3], 0, s[10:11]
	s_add_i32 m0, s3, 0x4000
	v_lshl_add_u64 v[2:3], v[2:3], 0, s[16:17]
	global_load_lds_dwordx4 v[6:7], off
	s_add_i32 m0, s3, 0x4400
	v_add_u32_e32 v0, s18, v228
	global_load_lds_dwordx4 v[2:3], off
	v_lshl_add_u64 v[2:3], v[4:5], 0, s[10:11]
	s_add_i32 s10, 0, 0x10000
	v_readlane_b32 s11, v254, 22
	s_add_i32 m0, s10, s11
	v_readlane_b32 s11, v254, 23
	v_lshl_add_u64 v[2:3], v[4:5], 0, s[16:17]
	s_add_i32 m0, s10, s11
	v_mov_b32_e32 v14, v1
	v_mov_b32_e32 v15, v1
	v_lshl_add_u64 v[202:203], v[198:199], 0, s[0:1]
	v_lshl_add_u64 v[204:205], v[200:201], 0, s[0:1]
	v_sub_u32_e32 v231, v219, v0
	v_readlane_b32 s0, v254, 48
	v_mov_b32_e32 v0, v1
	v_mov_b32_e32 v2, v1
	v_mov_b32_e32 v3, v1
	v_mov_b32_e32 v4, v1
	v_mov_b32_e32 v5, v1
	v_mov_b32_e32 v6, v1
	v_mov_b32_e32 v7, v1
	v_mov_b32_e32 v8, v1
	v_mov_b32_e32 v9, v1
	v_mov_b32_e32 v10, v1
	v_mov_b32_e32 v11, v1
	v_mov_b32_e32 v12, v1
	v_mov_b32_e32 v13, v1
	v_mov_b64_e32 v[30:31], v[14:15]
	v_mov_b64_e32 v[46:47], v[14:15]
	v_mov_b64_e32 v[62:63], v[14:15]
	v_mov_b64_e32 v[78:79], v[14:15]
	v_subrev_u32_e32 v230, s18, v227
	s_sub_i32 s40, s0, s18
	s_lshl_b32 s41, s39, 6
	s_mov_b32 s44, 0
	s_mov_b32 s50, -1
	v_mov_b32_e32 v232, 0
	s_mov_b64 s[16:17], 0
	s_mov_b32 s45, 2
	v_mov_b32_e32 v112, 0
	v_mov_b32_e32 v113, 0
	v_mov_b32_e32 v114, 0
	v_mov_b32_e32 v115, 0
	v_mov_b32_e32 v116, 0
	v_mov_b32_e32 v117, 0
	v_mov_b32_e32 v118, 0
	v_mov_b32_e32 v119, 0
	v_mov_b32_e32 v136, 0
	v_mov_b32_e32 v137, 0
	v_mov_b32_e32 v138, 0
	v_mov_b32_e32 v139, 0
	v_mov_b32_e32 v140, 0
	v_mov_b32_e32 v141, 0
	v_mov_b32_e32 v142, 0
	v_mov_b32_e32 v143, 0
	v_mov_b64_e32 v[28:29], v[12:13]
	v_mov_b64_e32 v[26:27], v[10:11]
	v_mov_b64_e32 v[24:25], v[8:9]
	v_mov_b64_e32 v[22:23], v[6:7]
	v_mov_b64_e32 v[20:21], v[4:5]
	v_mov_b64_e32 v[18:19], v[2:3]
	v_mov_b64_e32 v[16:17], v[0:1]
	v_mov_b64_e32 v[44:45], v[12:13]
	v_mov_b64_e32 v[42:43], v[10:11]
	v_mov_b64_e32 v[40:41], v[8:9]
	v_mov_b64_e32 v[38:39], v[6:7]
	v_mov_b64_e32 v[36:37], v[4:5]
	v_mov_b64_e32 v[34:35], v[2:3]
	v_mov_b64_e32 v[32:33], v[0:1]
	v_mov_b64_e32 v[60:61], v[12:13]
	v_mov_b64_e32 v[58:59], v[10:11]
	v_mov_b64_e32 v[56:57], v[8:9]
	v_mov_b64_e32 v[54:55], v[6:7]
	v_mov_b64_e32 v[52:53], v[4:5]
	v_mov_b64_e32 v[50:51], v[2:3]
	v_mov_b64_e32 v[48:49], v[0:1]
	v_mov_b64_e32 v[76:77], v[12:13]
	v_mov_b64_e32 v[74:75], v[10:11]
	v_mov_b64_e32 v[72:73], v[8:9]
	v_mov_b64_e32 v[70:71], v[6:7]
	v_mov_b64_e32 v[68:69], v[4:5]
	v_mov_b64_e32 v[66:67], v[2:3]
	v_mov_b64_e32 v[64:65], v[0:1]
	v_mov_b32_e32 v229, 0
	v_mov_b32_e32 v233, 0
	v_mov_b32_e32 v14, 0
	s_mov_b32 s46, 0
	s_mov_b32 s47, 2
	s_waitcnt vmcnt(0)
	s_barrier
	s_sub_i32 s19, 0xffffff42, s40
	s_sub_i32 s32, 0x9f, s40
	s_add_i32 s20, s41, 0xffffff80
	s_cmp_ge_i32 s44, s19
	s_cselect_b32 s0, 1, 0
	s_cmp_ge_i32 s44, s32
	s_addc_u32 s51, s0, 0
	s_mov_b64 s[0:1], 0x1b208000
	v_lshl_add_u64 v[204:205], v[204:205], 0, s[0:1]
	s_mov_b64 s[0:1], 0x27204000
	v_lshl_add_u64 v[202:203], v[202:203], 0, s[0:1]
	s_nop 0
	v_readfirstlane_b32 s68, v204
	v_readfirstlane_b32 s69, v205
	v_readfirstlane_b32 s74, v202
	v_readfirstlane_b32 s75, v203
	v_add_u32_e32 v204, 0x1000, v194
	v_add_u32_e32 v205, 0x1000, v196
	s_mov_b32 s18, 0xff800000
	s_mov_b32 s21, 0
	v_add_u32_e32 v253, v216, v191
	v_add_u32_e32 v252, v216, v218
	ds_read_b128 v[172:175], v253
	ds_read_b128 v[176:179], v252
	ds_read_b128 v[168:171], v253 offset:4096
	ds_read_b128 v[164:167], v252 offset:4096
	s_waitcnt lgkmcnt(0)
	v_mov_b32_e32 v0, 0
	v_mov_b32_e32 v2, 0
	v_mov_b32_e32 v3, 0
	v_mov_b32_e32 v5, 0
	v_mov_b32_e32 v6, 0
	v_mov_b32_e32 v7, 0
	v_mov_b32_e32 v8, 0
	v_mov_b32_e32 v9, 0
	v_mov_b32_e32 v10, 0
	v_mov_b32_e32 v15, 0
	v_mov_b32_e32 v80, 0
	v_mov_b32_e32 v81, 0
	v_mov_b32_e32 v82, 0
	v_mov_b32_e32 v83, 0
	v_mov_b32_e32 v84, 0
	v_mov_b32_e32 v85, 0
	v_mov_b32_e32 v86, 0
	v_mov_b32_e32 v87, 0
	v_mov_b32_e32 v184, 0
	v_mov_b32_e32 v185, 0
	v_mov_b32_e32 v209, 0
	v_mov_b32_e32 v235, 0
	v_mov_b32_e32 v144, 0
	v_mov_b32_e32 v145, 0
	v_mov_b32_e32 v146, 0
	v_mov_b32_e32 v147, 0
	v_mov_b32_e32 v156, 0
	v_mov_b32_e32 v157, 0
	v_mov_b32_e32 v158, 0
	v_mov_b32_e32 v159, 0
	v_mov_b32_e32 v160, 0
	v_mov_b32_e32 v161, 0
	s_branch .LBB0_204

; __device__ __forceinline__ void da_phase(LAS unsigned char* lds, const bf16* Q, const bf16* Kb, const bf16* Vb, bf16* O, const float* lq1, const float* lk1, const float* lq2, const float* lk2,
;                                          const float* t5, int G, int wave, int lane, int tid) {
;     ...
;         for (int t = 0; t < NT; ++t) {
;             if (t + 1 < NT) asm volatile("s_waitcnt vmcnt(4)" ::: "memory"); else asm volatile("s_waitcnt vmcnt(0)" ::: "memory");
;             __builtin_amdgcn_s_barrier();
;     ...
;             const int kv0 = 64 * t; const int relmin = kv0 - (qrow0 + 31), relmax = kv0 + 63 - qrow0;
;             const int cls = 1 + (relmin >= 128 ? 1 : 0) - (relmax <= -128 ? 1 : 0);
;     ...
;             ks_cur = (ks_cur == 2) ? 0 : ks_cur + 1; ks_n2 = (ks_n2 == 2) ? 0 : ks_n2 + 1;
.LBB0_203:
	s_cmp_ge_i32 s44, s20
	s_cbranch_scc1 .Lda_mid_v0
	s_waitcnt vmcnt(4)
.Lda_mid_bar:
	s_waitcnt lgkmcnt(0)
	s_barrier
	v_mfma_f32_32x32x16_bf16 v[64:79], v[140:143], v[160:163], v[64:79]
	v_exp_f32_e32 v0, v96
	v_exp_f32_e32 v15, v97
	s_add_i32 s0, s46, 1
	v_add_f32_e32 v96, v15, v0
	s_cmp_lg_u32 s46, 2
	s_cselect_b32 s46, s0, 0
	v_lshl_add_u32 v252, s46, 14, v216
	v_add_u32_e32 v253, v252, v191
	v_add_u32_e32 v252, v252, v218
	v_mfma_f32_32x32x16_bf16 v[64:79], v[136:139], v[156:159], v[64:79]
	v_exp_f32_e32 v156, v98
	v_exp_f32_e32 v157, v99
	v_add_f32_e32 v96, v156, v96
	v_add_f32_e32 v96, v157, v96
	ds_read_b128 v[172:175], v253
	ds_read_b128 v[176:179], v252
	ds_read_b128 v[168:171], v253 offset:4096
	ds_read_b128 v[164:167], v252 offset:4096
	v_mfma_f32_32x32x16_bf16 v[64:79], v[116:119], v[152:155], v[64:79]
	v_exp_f32_e32 v158, v100
	v_exp_f32_e32 v159, v101
	v_add_f32_e32 v96, v158, v96
	v_add_f32_e32 v96, v159, v96
	s_add_i32 s0, s47, 1
	s_cmp_lg_u32 s47, 2
	s_cselect_b32 s47, s0, 0
	s_and_b32 s21, s16, 0xc000
	v_mfma_f32_32x32x16_bf16 v[64:79], v[112:115], v[148:151], v[64:79]
	v_exp_f32_e32 v160, v102
	v_exp_f32_e32 v161, v103
	v_add_f32_e32 v162, v160, v96
	ds_read_b64_tr_b16 v[96:97], v234 offset:8192
	ds_read_b64_tr_b16 v[98:99], v234 offset:8704
	ds_read_b64_tr_b16 v[100:101], v234 offset:9216
	ds_read_b64_tr_b16 v[102:103], v234 offset:9728
	ds_read_b64_tr_b16 v[148:149], v234 offset:10240
	ds_read_b64_tr_b16 v[150:151], v234 offset:10752
	ds_read_b64_tr_b16 v[152:153], v234 offset:11264
	ds_read_b64_tr_b16 v[154:155], v234 offset:11776
	v_add_f32_e32 v162, v161, v162
	v_mfma_f32_32x32x16_bf16 v[48:63], v[140:143], v[144:147], v[48:63]
	v_exp_f32_e32 v144, v104
	v_exp_f32_e32 v145, v105
	v_add_f32_e32 v104, v144, v162
	v_add_f32_e32 v104, v145, v104
	s_add_i32 s16, s16, 0x4000
	s_add_i32 s44, s44, 64
	v_mfma_f32_32x32x16_bf16 v[48:63], v[136:139], v[10:13], v[48:63]
	v_exp_f32_e32 v146, v106
	v_exp_f32_e32 v147, v107
	v_add_f32_e32 v10, v146, v104
	v_add_f32_e32 v10, v147, v10
	s_cmp_ge_i32 s44, s19
	s_cselect_b32 s0, 1, 0
	s_cmp_ge_i32 s44, s32
	s_addc_u32 s51, s0, 0
	v_mfma_f32_32x32x16_bf16 v[48:63], v[116:119], v[6:9], v[48:63]
	v_exp_f32_e32 v184, v108
	v_exp_f32_e32 v185, v109
	v_add_f32_e32 v6, v184, v10
	v_add_f32_e32 v6, v185, v6
	v_mfma_f32_32x32x16_bf16 v[48:63], v[112:115], v[2:5], v[48:63]
	v_exp_f32_e32 v209, v110
	v_exp_f32_e32 v235, v111
	v_add_f32_e32 v162, v209, v6
	ds_read_b64_tr_b16 v[2:3], v234 offset:12288
	ds_read_b64_tr_b16 v[4:5], v234 offset:12800
	ds_read_b64_tr_b16 v[6:7], v234 offset:13312
	ds_read_b64_tr_b16 v[8:9], v234 offset:13824
	ds_read_b64_tr_b16 v[10:11], v234 offset:14336
	ds_read_b64_tr_b16 v[12:13], v234 offset:14848
	ds_read_b64_tr_b16 v[104:105], v234 offset:15360
	ds_read_b64_tr_b16 v[106:107], v234 offset:15872
	s_waitcnt lgkmcnt(8)
	v_add_f32_e32 v162, v235, v162
	v_mfma_f32_32x32x16_bf16 v[32:47], v[140:143], v[96:99], v[32:47]
	v_exp_f32_e32 v80, v80
	v_exp_f32_e32 v81, v81
	v_add_f32_e32 v96, v80, v162
	v_add_f32_e32 v96, v81, v96
	v_mfma_f32_32x32x16_bf16 v[32:47], v[136:139], v[100:103], v[32:47]
	v_exp_f32_e32 v82, v82
	v_exp_f32_e32 v83, v83
	v_add_f32_e32 v96, v82, v96
	v_add_f32_e32 v96, v83, v96
	v_mfma_f32_32x32x16_bf16 v[32:47], v[116:119], v[148:151], v[32:47]
	v_exp_f32_e32 v84, v84
	v_exp_f32_e32 v85, v85
	v_add_f32_e32 v96, v84, v96
	v_add_f32_e32 v96, v85, v96
	v_mfma_f32_32x32x16_bf16 v[32:47], v[112:115], v[152:155], v[32:47]
	v_exp_f32_e32 v86, v86
	v_exp_f32_e32 v87, v87
	v_add_f32_e32 v96, v86, v96
	v_add_f32_e32 v96, v87, v96
	s_waitcnt lgkmcnt(0)
	v_mfma_f32_32x32x16_bf16 v[16:31], v[140:143], v[2:5], v[16:31]
	v_exp_f32_e32 v2, v88
	v_exp_f32_e32 v3, v89
	v_add_f32_e32 v4, v2, v96
	v_add_f32_e32 v4, v3, v4
	v_mfma_f32_32x32x16_bf16 v[16:31], v[136:139], v[6:9], v[16:31]
	v_exp_f32_e32 v5, v90
	v_exp_f32_e32 v6, v91
	v_add_f32_e32 v4, v5, v4
	v_add_f32_e32 v4, v6, v4
	v_mfma_f32_32x32x16_bf16 v[16:31], v[116:119], v[10:13], v[16:31]
	v_exp_f32_e32 v7, v92
	v_exp_f32_e32 v8, v93
	v_add_f32_e32 v4, v7, v4
	v_add_f32_e32 v4, v8, v4
	v_mfma_f32_32x32x16_bf16 v[16:31], v[112:115], v[104:107], v[16:31]
	v_exp_f32_e32 v9, v94
	v_exp_f32_e32 v10, v95
	v_add_f32_e32 v4, v9, v4
	v_add_f32_e32 v4, v10, v4
	v_add_f32_e32 v229, v229, v4
	s_cmp_eq_u32 s41, s44
	s_cbranch_scc1 .LBB0_228

; #define DS_RD128(dst, addr, off) asm volatile("ds_read_b128 %0, %1 offset:%c2" : "=v"(dst) : "v"(addr), "i"(off) : "memory")
; __device__ __forceinline__ void da_phase(LAS unsigned char* lds, const bf16* Q, const bf16* Kb, const bf16* Vb, bf16* O, const float* lq1, const float* lk1, const float* lq2, const float* lk2,
;                                          const float* t5, int G, int wave, int lane, int tid) {
;     ...
;             F16 p0, p1;
;             {   typedef float F2i __attribute__((ext_vector_type(2))); F2i c2 = {cbm, cbm}; asm volatile("" : "+v"(c2));
; #pragma unroll
;                 for (int r = 0; r < 16; r += 2) { p0[r] = c2.x; p0[r + 1] = c2.y; p1[r] = c2.x; p1[r + 1] = c2.y; } }
;             asm volatile("s_waitcnt lgkmcnt(15)" ::: "memory"); SCHED_FENCE();
; #pragma unroll
;             for (int d0 = 0; d0 < 4; ++d0) p0 = __builtin_amdgcn_mfma_f32_32x32x16_bf16(__builtin_bit_cast(H8, kf[d0]), qf[d0], p0, 0, 0, 0);
;             SCHED_FENCE();
;             DS_RD128(kf[0], ka0, 2048); DS_RD128(kf[1], ka1, 2048); DS_RD128(kf[2], ka0, 6144); DS_RD128(kf[3], ka1, 6144);
;             if (t + 2 < NT) DA_DMA_K(t + 2, ks_n2);
;             LGKM_WAIT(0); SCHED_FENCE();
;             float a0;
;             p1 = __builtin_amdgcn_mfma_f32_32x32x16_bf16(__builtin_bit_cast(H8, kf[0]), qf[0], p1, 0, 0, 0); a0 = __builtin_fmaxf(__builtin_fmaxf(p0[0], p0[1]), p0[2]); a0 = __builtin_fmaxf(__builtin_fmaxf(a0, p0[3]), p0[4]); asm volatile("" : "+v"(a0)); SCHED_FENCE();
;             p1 = __builtin_amdgcn_mfma_f32_32x32x16_bf16(__builtin_bit_cast(H8, kf[1]), qf[1], p1, 0, 0, 0); a0 = __builtin_fmaxf(__builtin_fmaxf(a0, p0[5]), p0[6]); a0 = __builtin_fmaxf(__builtin_fmaxf(a0, p0[7]), p0[8]); asm volatile("" : "+v"(a0)); SCHED_FENCE();
;             p1 = __builtin_amdgcn_mfma_f32_32x32x16_bf16(__builtin_bit_cast(H8, kf[2]), qf[2], p1, 0, 0, 0); a0 = __builtin_fmaxf(__builtin_fmaxf(a0, p0[9]), p0[10]); a0 = __builtin_fmaxf(__builtin_fmaxf(a0, p0[11]), p0[12]); asm volatile("" : "+v"(a0)); SCHED_FENCE();
;             p1 = __builtin_amdgcn_mfma_f32_32x32x16_bf16(__builtin_bit_cast(H8, kf[3]), qf[3], p1, 0, 0, 0); a0 = __builtin_fmaxf(__builtin_fmaxf(a0, p0[13]), p0[14]); a0 = __builtin_fmaxf(a0, p0[15]); asm volatile("" : "+v"(a0)); SCHED_FENCE();
;             if (t + 2 < NT) DA_DMA_V(t + 2, (t + 2) & 3);
.LBB0_215:
	v_mfma_f32_32x32x16_bf16 v[96:111], v[172:175], v[120:123], v[236:251]
	ds_read_b128 v[172:175], v252 offset:2048
	v_cvt_pk_bf16_f32 v140, v0, v15
	v_cvt_pk_bf16_f32 v141, v156, v157
	v_cvt_pk_bf16_f32 v142, v158, v159
	v_cvt_pk_bf16_f32 v143, v160, v161
	v_mfma_f32_32x32x16_bf16 v[96:111], v[176:179], v[124:127], v[96:111]
	ds_read_b128 v[176:179], v253 offset:2048
	v_cvt_pk_bf16_f32 v136, v144, v145
	v_cvt_pk_bf16_f32 v137, v146, v147
	v_cvt_pk_bf16_f32 v138, v184, v185
	v_cvt_pk_bf16_f32 v139, v209, v235
	v_mfma_f32_32x32x16_bf16 v[96:111], v[168:171], v[128:131], v[96:111]
	ds_read_b128 v[168:171], v253 offset:6144
	v_cvt_pk_bf16_f32 v116, v80, v81
	v_cvt_pk_bf16_f32 v117, v82, v83
	v_cvt_pk_bf16_f32 v118, v84, v85
	v_cvt_pk_bf16_f32 v119, v86, v87
	v_mfma_f32_32x32x16_bf16 v[96:111], v[164:167], v[132:135], v[96:111]
	ds_read_b128 v[164:167], v252 offset:6144
	v_cvt_pk_bf16_f32 v112, v2, v3
	v_cvt_pk_bf16_f32 v113, v5, v6
	v_cvt_pk_bf16_f32 v114, v7, v8
	v_cvt_pk_bf16_f32 v115, v9, v10
	s_cmp_ge_i32 s44, s20
	s_cbranch_scc1 .LBB0_217
	s_lshl_b32 s0, s47, 14
	s_add_i32 m0, s3, s0
	s_nop 0
	global_load_lds_dwordx4 v194, s[68:69]
	s_add_i32 m0, m0, 0x400
	s_nop 0
	global_load_lds_dwordx4 v204, s[68:69]
	s_add_u32 s68, s68, 0x4000
	s_addc_u32 s69, s69, 0
.LBB0_217:
	s_waitcnt lgkmcnt(0)
	v_mfma_f32_32x32x16_bf16 v[80:95], v[176:179], v[120:123], v[236:251]
	ds_read_b64_tr_b16 v[160:161], v234 offset:0
	ds_read_b64_tr_b16 v[162:163], v234 offset:512
	ds_read_b64_tr_b16 v[156:157], v234 offset:1024
	ds_read_b64_tr_b16 v[158:159], v234 offset:1536
	v_max3_f32 v0, v96, v97, v98
	v_max3_f32 v0, v0, v99, v100
	v_mfma_f32_32x32x16_bf16 v[80:95], v[172:175], v[124:127], v[80:95]
	ds_read_b64_tr_b16 v[152:153], v234 offset:2048
	ds_read_b64_tr_b16 v[154:155], v234 offset:2560
	ds_read_b64_tr_b16 v[148:149], v234 offset:3072
	ds_read_b64_tr_b16 v[150:151], v234 offset:3584
	v_max3_f32 v0, v0, v101, v102
	v_max3_f32 v0, v0, v103, v104
	v_mfma_f32_32x32x16_bf16 v[80:95], v[168:171], v[128:131], v[80:95]
	ds_read_b64_tr_b16 v[144:145], v234 offset:4096
	ds_read_b64_tr_b16 v[146:147], v234 offset:4608
	ds_read_b64_tr_b16 v[10:11], v234 offset:5120
	ds_read_b64_tr_b16 v[12:13], v234 offset:5632
	v_max3_f32 v0, v0, v105, v106
	v_max3_f32 v0, v0, v107, v108
	v_mfma_f32_32x32x16_bf16 v[80:95], v[164:167], v[132:135], v[80:95]
	ds_read_b64_tr_b16 v[6:7], v234 offset:6144
	ds_read_b64_tr_b16 v[8:9], v234 offset:6656
	ds_read_b64_tr_b16 v[2:3], v234 offset:7168
	ds_read_b64_tr_b16 v[4:5], v234 offset:7680
	v_max_f32_e32 v0, v0, v0
	v_max_f32_e32 v15, v109, v109
	v_max_f32_e32 v0, v0, v15
	v_max3_f32 v0, v0, v110, v111
	s_cmp_gt_i32 s44, s20
	s_cbranch_scc1 .Lda_vskip
	s_add_i32 s0, s16, 0x4000
	s_and_b32 s0, s0, 0xc000
	s_add_i32 s0, s3, s0
	s_add_i32 m0, s0, 0xc000
	s_nop 0
	global_load_lds_dwordx4 v196, s[74:75]
	s_add_i32 m0, m0, 0x400
	s_nop 0
	global_load_lds_dwordx4 v205, s[74:75]
	s_add_u32 s74, s74, 0x4000
	s_addc_u32 s75, s75, 0
